# E1 layer-0 norm: contiguous 16B/lane mapping (1 KB per load instruction)
# speedup vs baseline: 1.0065x; 1.0065x over previous
.LBB0_581:
.LBB0_582:
	v_mov_b32_e32 v0, v160
	s_and_b64 vcc, exec, s[36:37]
	s_cbranch_vccnz .LBB0_589
	v_lshlrev_b32_e32 v96, 4, v204
	v_lshlrev_b32_e32 v97, 3, v204
	v_readlane_b32 s14, v243, 0
	v_readlane_b32 s38, v247, 30
	v_readlane_b32 s39, v247, 31
	s_nop 7
	global_load_dwordx4 v[64:67], v96, s[38:39]
	global_load_dwordx4 v[68:71], v96, s[38:39] offset:1024
	global_load_dwordx4 v[72:75], v96, s[38:39] offset:2048
	global_load_dwordx4 v[76:79], v96, s[38:39] offset:3072
	s_mov_b32 s26, 0x3a800000

.Le1a_adr:
	s_nop 3
	s_lshr_b32 s39, s38, 20
	s_lshl_b32 s38, s38, 12
	s_add_u32 s0, s0, s38
	s_addc_u32 s1, s1, s39
	s_add_u32 s2, s0, 0x1000
	s_addc_u32 s3, s1, 0
	s_add_u32 s6, s0, 0x2000
	s_addc_u32 s7, s1, 0
	s_add_u32 s8, s0, 0x3000
	s_addc_u32 s9, s1, 0
	global_load_dwordx4 v[100:103], v96, s[0:1]
	global_load_dwordx4 v[104:107], v96, s[0:1] offset:1024
	global_load_dwordx4 v[108:111], v96, s[0:1] offset:2048
	global_load_dwordx4 v[112:115], v96, s[0:1] offset:3072
	global_load_dwordx4 v[116:119], v96, s[2:3]
	global_load_dwordx4 v[120:123], v96, s[2:3] offset:1024
	global_load_dwordx4 v[124:127], v96, s[2:3] offset:2048
	global_load_dwordx4 v[128:131], v96, s[2:3] offset:3072
	global_load_dwordx4 v[132:135], v96, s[6:7]
	global_load_dwordx4 v[136:139], v96, s[6:7] offset:1024
	global_load_dwordx4 v[140:143], v96, s[6:7] offset:2048
	global_load_dwordx4 v[144:147], v96, s[6:7] offset:3072
	global_load_dwordx4 v[148:151], v96, s[8:9]
	global_load_dwordx4 v[152:155], v96, s[8:9] offset:1024
	global_load_dwordx4 v[156:159], v96, s[8:9] offset:2048
	global_load_dwordx4 v[164:167], v96, s[8:9] offset:3072
	s_mul_i32 s38, s15, 0x6000
	s_add_u32 s12, s30, s38
	s_addc_u32 s13, s31, 0
	s_add_u32 s8, s12, 0x1000
	s_addc_u32 s9, s13, 0
	global_load_dwordx4 v[32:35], v96, s[8:9]
	global_load_dwordx4 v[36:39], v96, s[8:9] offset:1024
	global_load_dwordx4 v[40:43], v96, s[8:9] offset:2048
	global_load_dwordx4 v[44:47], v96, s[8:9] offset:3072
	global_load_dwordx4 v[48:51], v96, s[12:13]
	global_load_dwordx4 v[52:55], v96, s[12:13] offset:1024
	global_load_dwordx4 v[56:59], v96, s[12:13] offset:2048
	global_load_dwordx4 v[60:63], v96, s[12:13] offset:3072
	s_lshl_b32 s38, s14, 11
	s_add_u32 s4, s84, 0x4b00000
	s_addc_u32 s5, s85, 0
	s_add_u32 s4, s4, s38
	s_addc_u32 s5, s5, 0
	s_add_u32 s6, s4, 0x1000
	s_addc_u32 s7, s5, 0
	s_waitcnt vmcnt(8)
	v_mul_f32_e32 v80, v100, v100
	v_mul_f32_e32 v81, v116, v116
	v_mul_f32_e32 v82, v132, v132
	v_mul_f32_e32 v83, v148, v148
	v_fmac_f32_e32 v80, v101, v101
	v_fmac_f32_e32 v81, v117, v117
	v_fmac_f32_e32 v82, v133, v133
	v_fmac_f32_e32 v83, v149, v149
	v_fmac_f32_e32 v80, v102, v102
	v_fmac_f32_e32 v81, v118, v118
	v_fmac_f32_e32 v82, v134, v134
	v_fmac_f32_e32 v83, v150, v150
	v_fmac_f32_e32 v80, v103, v103
	v_fmac_f32_e32 v81, v119, v119
	v_fmac_f32_e32 v82, v135, v135
	v_fmac_f32_e32 v83, v151, v151
	v_fmac_f32_e32 v80, v104, v104
	v_fmac_f32_e32 v81, v120, v120
	v_fmac_f32_e32 v82, v136, v136
	v_fmac_f32_e32 v83, v152, v152
	v_fmac_f32_e32 v80, v105, v105
	v_fmac_f32_e32 v81, v121, v121
	v_fmac_f32_e32 v82, v137, v137
	v_fmac_f32_e32 v83, v153, v153
	v_fmac_f32_e32 v80, v106, v106
	v_fmac_f32_e32 v81, v122, v122
	v_fmac_f32_e32 v82, v138, v138
	v_fmac_f32_e32 v83, v154, v154
	v_fmac_f32_e32 v80, v107, v107
	v_fmac_f32_e32 v81, v123, v123
	v_fmac_f32_e32 v82, v139, v139
	v_fmac_f32_e32 v83, v155, v155
	v_fmac_f32_e32 v80, v108, v108
	v_fmac_f32_e32 v81, v124, v124
	v_fmac_f32_e32 v82, v140, v140
	v_fmac_f32_e32 v83, v156, v156
	v_fmac_f32_e32 v80, v109, v109
	v_fmac_f32_e32 v81, v125, v125
	v_fmac_f32_e32 v82, v141, v141
	v_fmac_f32_e32 v83, v157, v157
	v_fmac_f32_e32 v80, v110, v110
	v_fmac_f32_e32 v81, v126, v126
	v_fmac_f32_e32 v82, v142, v142
	v_fmac_f32_e32 v83, v158, v158
	v_fmac_f32_e32 v80, v111, v111
	v_fmac_f32_e32 v81, v127, v127
	v_fmac_f32_e32 v82, v143, v143
	v_fmac_f32_e32 v83, v159, v159
	v_fmac_f32_e32 v80, v112, v112
	v_fmac_f32_e32 v81, v128, v128
	v_fmac_f32_e32 v82, v144, v144
	v_fmac_f32_e32 v83, v164, v164
	v_fmac_f32_e32 v80, v113, v113
	v_fmac_f32_e32 v81, v129, v129
	v_fmac_f32_e32 v82, v145, v145
	v_fmac_f32_e32 v83, v165, v165
	v_fmac_f32_e32 v80, v114, v114
	v_fmac_f32_e32 v81, v130, v130
	v_fmac_f32_e32 v82, v146, v146
	v_fmac_f32_e32 v83, v166, v166
	v_fmac_f32_e32 v80, v115, v115
	v_fmac_f32_e32 v81, v131, v131
	v_fmac_f32_e32 v82, v147, v147
	v_fmac_f32_e32 v83, v167, v167
	v_add_f32_dpp v80, v80, v80 quad_perm:[1,0,3,2] row_mask:0xf bank_mask:0xf
	v_add_f32_dpp v81, v81, v81 quad_perm:[1,0,3,2] row_mask:0xf bank_mask:0xf
	v_add_f32_dpp v82, v82, v82 quad_perm:[1,0,3,2] row_mask:0xf bank_mask:0xf
	v_add_f32_dpp v83, v83, v83 quad_perm:[1,0,3,2] row_mask:0xf bank_mask:0xf
	s_nop 0
	v_add_f32_dpp v80, v80, v80 quad_perm:[2,3,0,1] row_mask:0xf bank_mask:0xf
	v_add_f32_dpp v81, v81, v81 quad_perm:[2,3,0,1] row_mask:0xf bank_mask:0xf
	v_add_f32_dpp v82, v82, v82 quad_perm:[2,3,0,1] row_mask:0xf bank_mask:0xf
	v_add_f32_dpp v83, v83, v83 quad_perm:[2,3,0,1] row_mask:0xf bank_mask:0xf
	s_nop 0
	v_add_f32_dpp v80, v80, v80 row_half_mirror row_mask:0xf bank_mask:0xf
	v_add_f32_dpp v81, v81, v81 row_half_mirror row_mask:0xf bank_mask:0xf
	v_add_f32_dpp v82, v82, v82 row_half_mirror row_mask:0xf bank_mask:0xf
	v_add_f32_dpp v83, v83, v83 row_half_mirror row_mask:0xf bank_mask:0xf
	s_nop 0
	v_add_f32_dpp v80, v80, v80 row_mirror row_mask:0xf bank_mask:0xf
	v_add_f32_dpp v81, v81, v81 row_mirror row_mask:0xf bank_mask:0xf
	v_add_f32_dpp v82, v82, v82 row_mirror row_mask:0xf bank_mask:0xf
	v_add_f32_dpp v83, v83, v83 row_mirror row_mask:0xf bank_mask:0xf
	s_nop 0
	v_add_f32_dpp v80, v80, v80 row_bcast:15 row_mask:0xa bank_mask:0xf
	v_add_f32_dpp v81, v81, v81 row_bcast:15 row_mask:0xa bank_mask:0xf
	v_add_f32_dpp v82, v82, v82 row_bcast:15 row_mask:0xa bank_mask:0xf
	v_add_f32_dpp v83, v83, v83 row_bcast:15 row_mask:0xa bank_mask:0xf
	s_nop 0
	v_add_f32_dpp v80, v80, v80 row_bcast:31 row_mask:0xc bank_mask:0xf
	v_add_f32_dpp v81, v81, v81 row_bcast:31 row_mask:0xc bank_mask:0xf
	v_add_f32_dpp v82, v82, v82 row_bcast:31 row_mask:0xc bank_mask:0xf
	v_add_f32_dpp v83, v83, v83 row_bcast:31 row_mask:0xc bank_mask:0xf
	s_nop 0
	v_mov_b32_e32 v92, 0x358637bd
	s_nop 0
	v_fma_f32 v80, v80, s26, v92
	v_fma_f32 v81, v81, s26, v92
	v_fma_f32 v82, v82, s26, v92
	v_fma_f32 v83, v83, s26, v92
	v_rsq_f32_e32 v80, v80
	v_rsq_f32_e32 v81, v81
	v_rsq_f32_e32 v82, v82
	v_rsq_f32_e32 v83, v83
	s_nop 1
	v_readlane_b32 s16, v80, 63
	v_readlane_b32 s17, v81, 63
	v_readlane_b32 s18, v82, 63
	v_readlane_b32 s19, v83, 63
	s_waitcnt vmcnt(0)
	v_add_f32_e32 v32, 1.0, v32
	v_add_f32_e32 v33, 1.0, v33
	v_add_f32_e32 v34, 1.0, v34
	v_add_f32_e32 v35, 1.0, v35
	v_add_f32_e32 v36, 1.0, v36
	v_add_f32_e32 v37, 1.0, v37
	v_add_f32_e32 v38, 1.0, v38
	v_add_f32_e32 v39, 1.0, v39
	v_add_f32_e32 v40, 1.0, v40
	v_add_f32_e32 v41, 1.0, v41
	v_add_f32_e32 v42, 1.0, v42
	v_add_f32_e32 v43, 1.0, v43
	v_add_f32_e32 v44, 1.0, v44
	v_add_f32_e32 v45, 1.0, v45
	v_add_f32_e32 v46, 1.0, v46
	v_add_f32_e32 v47, 1.0, v47
	v_mul_f32_e32 v32, v64, v32
	v_mul_f32_e32 v33, v65, v33
	v_mul_f32_e32 v34, v66, v34
	v_mul_f32_e32 v35, v67, v35
	v_mul_f32_e32 v36, v68, v36
	v_mul_f32_e32 v37, v69, v37
	v_mul_f32_e32 v38, v70, v38
	v_mul_f32_e32 v39, v71, v39
	v_mul_f32_e32 v40, v72, v40
	v_mul_f32_e32 v41, v73, v41
	v_mul_f32_e32 v42, v74, v42
	v_mul_f32_e32 v43, v75, v43
	v_mul_f32_e32 v44, v76, v44
	v_mul_f32_e32 v45, v77, v45
	v_mul_f32_e32 v46, v78, v46
	v_mul_f32_e32 v47, v79, v47
	v_mul_f32_e32 v100, s16, v100
	v_mul_f32_e32 v101, s16, v101
	v_fma_f32 v100, v100, v32, v48
	v_fma_f32 v101, v101, v33, v49
	v_cvt_pk_bf16_f32 v0, v100, v101
	v_mul_f32_e32 v102, s16, v102
	v_mul_f32_e32 v103, s16, v103
	v_fma_f32 v102, v102, v34, v50
	v_fma_f32 v103, v103, v35, v51
	v_cvt_pk_bf16_f32 v1, v102, v103
	global_store_dwordx2 v97, v[0:1], s[4:5]
	v_mul_f32_e32 v104, s16, v104
	v_mul_f32_e32 v105, s16, v105
	v_fma_f32 v104, v104, v36, v52
	v_fma_f32 v105, v105, v37, v53
	v_cvt_pk_bf16_f32 v2, v104, v105
	v_mul_f32_e32 v106, s16, v106
	v_mul_f32_e32 v107, s16, v107
	v_fma_f32 v106, v106, v38, v54
	v_fma_f32 v107, v107, v39, v55
	v_cvt_pk_bf16_f32 v3, v106, v107
	global_store_dwordx2 v97, v[2:3], s[4:5] offset:512
	v_mul_f32_e32 v108, s16, v108
	v_mul_f32_e32 v109, s16, v109
	v_fma_f32 v108, v108, v40, v56
	v_fma_f32 v109, v109, v41, v57
	v_cvt_pk_bf16_f32 v4, v108, v109
	v_mul_f32_e32 v110, s16, v110
	v_mul_f32_e32 v111, s16, v111
	v_fma_f32 v110, v110, v42, v58
	v_fma_f32 v111, v111, v43, v59
	v_cvt_pk_bf16_f32 v5, v110, v111
	global_store_dwordx2 v97, v[4:5], s[4:5] offset:1024
	v_mul_f32_e32 v112, s16, v112
	v_mul_f32_e32 v113, s16, v113
	v_fma_f32 v112, v112, v44, v60
	v_fma_f32 v113, v113, v45, v61
	v_cvt_pk_bf16_f32 v6, v112, v113
	v_mul_f32_e32 v114, s16, v114
	v_mul_f32_e32 v115, s16, v115
	v_fma_f32 v114, v114, v46, v62
	v_fma_f32 v115, v115, v47, v63
	v_cvt_pk_bf16_f32 v7, v114, v115
	global_store_dwordx2 v97, v[6:7], s[4:5] offset:1536
	v_mul_f32_e32 v116, s17, v116
	v_mul_f32_e32 v117, s17, v117
	v_fma_f32 v116, v116, v32, v48
	v_fma_f32 v117, v117, v33, v49
	v_cvt_pk_bf16_f32 v8, v116, v117
	v_mul_f32_e32 v118, s17, v118
	v_mul_f32_e32 v119, s17, v119
	v_fma_f32 v118, v118, v34, v50
	v_fma_f32 v119, v119, v35, v51
	v_cvt_pk_bf16_f32 v9, v118, v119
	global_store_dwordx2 v97, v[8:9], s[4:5] offset:2048
	v_mul_f32_e32 v120, s17, v120
	v_mul_f32_e32 v121, s17, v121
	v_fma_f32 v120, v120, v36, v52
	v_fma_f32 v121, v121, v37, v53
	v_cvt_pk_bf16_f32 v10, v120, v121
	v_mul_f32_e32 v122, s17, v122
	v_mul_f32_e32 v123, s17, v123
	v_fma_f32 v122, v122, v38, v54
	v_fma_f32 v123, v123, v39, v55
	v_cvt_pk_bf16_f32 v11, v122, v123
	global_store_dwordx2 v97, v[10:11], s[4:5] offset:2560
	v_mul_f32_e32 v124, s17, v124
	v_mul_f32_e32 v125, s17, v125
	v_fma_f32 v124, v124, v40, v56
	v_fma_f32 v125, v125, v41, v57
	v_cvt_pk_bf16_f32 v12, v124, v125
	v_mul_f32_e32 v126, s17, v126
	v_mul_f32_e32 v127, s17, v127
	v_fma_f32 v126, v126, v42, v58
	v_fma_f32 v127, v127, v43, v59
	v_cvt_pk_bf16_f32 v13, v126, v127
	global_store_dwordx2 v97, v[12:13], s[4:5] offset:3072
	v_mul_f32_e32 v128, s17, v128
	v_mul_f32_e32 v129, s17, v129
	v_fma_f32 v128, v128, v44, v60
	v_fma_f32 v129, v129, v45, v61
	v_cvt_pk_bf16_f32 v14, v128, v129
	v_mul_f32_e32 v130, s17, v130
	v_mul_f32_e32 v131, s17, v131
	v_fma_f32 v130, v130, v46, v62
	v_fma_f32 v131, v131, v47, v63
	v_cvt_pk_bf16_f32 v15, v130, v131
	global_store_dwordx2 v97, v[14:15], s[4:5] offset:3584
	v_mul_f32_e32 v132, s18, v132
	v_mul_f32_e32 v133, s18, v133
	v_fma_f32 v132, v132, v32, v48
	v_fma_f32 v133, v133, v33, v49
	v_cvt_pk_bf16_f32 v16, v132, v133
	v_mul_f32_e32 v134, s18, v134
	v_mul_f32_e32 v135, s18, v135
	v_fma_f32 v134, v134, v34, v50
	v_fma_f32 v135, v135, v35, v51
	v_cvt_pk_bf16_f32 v17, v134, v135
	global_store_dwordx2 v97, v[16:17], s[6:7]
	v_mul_f32_e32 v136, s18, v136
	v_mul_f32_e32 v137, s18, v137
	v_fma_f32 v136, v136, v36, v52
	v_fma_f32 v137, v137, v37, v53
	v_cvt_pk_bf16_f32 v18, v136, v137
	v_mul_f32_e32 v138, s18, v138
	v_mul_f32_e32 v139, s18, v139
	v_fma_f32 v138, v138, v38, v54
	v_fma_f32 v139, v139, v39, v55
	v_cvt_pk_bf16_f32 v19, v138, v139
	global_store_dwordx2 v97, v[18:19], s[6:7] offset:512
	v_mul_f32_e32 v140, s18, v140
	v_mul_f32_e32 v141, s18, v141
	v_fma_f32 v140, v140, v40, v56
	v_fma_f32 v141, v141, v41, v57
	v_cvt_pk_bf16_f32 v20, v140, v141
	v_mul_f32_e32 v142, s18, v142
	v_mul_f32_e32 v143, s18, v143
	v_fma_f32 v142, v142, v42, v58
	v_fma_f32 v143, v143, v43, v59
	v_cvt_pk_bf16_f32 v21, v142, v143
	global_store_dwordx2 v97, v[20:21], s[6:7] offset:1024
	v_mul_f32_e32 v144, s18, v144
	v_mul_f32_e32 v145, s18, v145
	v_fma_f32 v144, v144, v44, v60
	v_fma_f32 v145, v145, v45, v61
	v_cvt_pk_bf16_f32 v22, v144, v145
	v_mul_f32_e32 v146, s18, v146
	v_mul_f32_e32 v147, s18, v147
	v_fma_f32 v146, v146, v46, v62
	v_fma_f32 v147, v147, v47, v63
	v_cvt_pk_bf16_f32 v23, v146, v147
	global_store_dwordx2 v97, v[22:23], s[6:7] offset:1536
	v_mul_f32_e32 v148, s19, v148
	v_mul_f32_e32 v149, s19, v149
	v_fma_f32 v148, v148, v32, v48
	v_fma_f32 v149, v149, v33, v49
	v_cvt_pk_bf16_f32 v24, v148, v149
	v_mul_f32_e32 v150, s19, v150
	v_mul_f32_e32 v151, s19, v151
	v_fma_f32 v150, v150, v34, v50
	v_fma_f32 v151, v151, v35, v51
	v_cvt_pk_bf16_f32 v25, v150, v151
	global_store_dwordx2 v97, v[24:25], s[6:7] offset:2048
	v_mul_f32_e32 v152, s19, v152
	v_mul_f32_e32 v153, s19, v153
	v_fma_f32 v152, v152, v36, v52
	v_fma_f32 v153, v153, v37, v53
	v_cvt_pk_bf16_f32 v26, v152, v153
	v_mul_f32_e32 v154, s19, v154
	v_mul_f32_e32 v155, s19, v155
	v_fma_f32 v154, v154, v38, v54
	v_fma_f32 v155, v155, v39, v55
	v_cvt_pk_bf16_f32 v27, v154, v155
	global_store_dwordx2 v97, v[26:27], s[6:7] offset:2560
	v_mul_f32_e32 v156, s19, v156
	v_mul_f32_e32 v157, s19, v157
	v_fma_f32 v156, v156, v40, v56
	v_fma_f32 v157, v157, v41, v57
	v_cvt_pk_bf16_f32 v28, v156, v157
	v_mul_f32_e32 v158, s19, v158
	v_mul_f32_e32 v159, s19, v159
	v_fma_f32 v158, v158, v42, v58
	v_fma_f32 v159, v159, v43, v59
	v_cvt_pk_bf16_f32 v29, v158, v159
	global_store_dwordx2 v97, v[28:29], s[6:7] offset:3072
	v_mul_f32_e32 v164, s19, v164
	v_mul_f32_e32 v165, s19, v165
	v_fma_f32 v164, v164, v44, v60
	v_fma_f32 v165, v165, v45, v61
	v_cvt_pk_bf16_f32 v30, v164, v165
	v_mul_f32_e32 v166, s19, v166
	v_mul_f32_e32 v167, s19, v167
	v_fma_f32 v166, v166, v46, v62
	v_fma_f32 v167, v167, v47, v63
	v_cvt_pk_bf16_f32 v31, v166, v167
	global_store_dwordx2 v97, v[30:31], s[6:7] offset:3584
	s_add_u32 s14, s14, s24
	s_cmp_lt_u32 s14, 0x8800
	s_cbranch_scc1 .Le1a_loop
	v_readlane_b32 s10, v242, 3
	v_readlane_b32 s11, v242, 4
